# attention: attn_norm weight loads issued right after the score row-max (400 instructions ahead of use)
# speedup vs baseline: 1.0010x; 1.0010x over previous
.LBB0_446:
	s_add_i32 s16, s16, s2
	s_max_i32 s11, s16, 4
	s_ashr_i32 s10, s15, 8
	s_add_i32 s11, s11, -4
	s_min_u32 s1, s17, 49
	s_min_u32 s12, s11, 56
	s_ashr_i32 s11, s10, 31
	s_and_b32 s0, s14, 48
	s_sub_i32 s13, s12, s1
	s_lshl_b64 s[10:11], s[10:11], 12
	s_lshl_b32 s1, s16, 6
	s_add_u32 s10, s10, s1
	s_addc_u32 s1, s11, 0
	s_lshl_b32 s46, s13, 12
	v_add_u32_e32 v83, s46, v182
	v_add_u32_e32 v129, v83, v177
	v_add_u32_e32 v131, v83, v178
	ds_read_b128 v[84:87], v129
	ds_read_b128 v[88:91], v129 offset:512
	ds_read_b128 v[92:95], v131
	ds_read_b128 v[96:99], v131 offset:512
	s_waitcnt vmcnt(18) lgkmcnt(3)
	v_mfma_f32_16x16x32_bf16 v[84:87], v[84:87], v[78:81], 0
	v_sub_u32_e64 v82, s0, 8 clamp
	v_min_u32_e32 v133, 32, v82
	v_or_b32_e32 v135, s0, v173
	s_waitcnt lgkmcnt(2)
	v_mfma_f32_16x16x32_bf16 v[88:91], v[88:91], v[78:81], 0
	s_or_b32 s0, s10, s0
	s_lshl_b64 s[0:1], s[0:1], 11
	s_add_i32 s47, s46, 0x1000
	s_waitcnt lgkmcnt(1)
	v_mfma_f32_16x16x32_bf16 v[188:191], v[92:95], v[74:77], v[84:87]
	s_add_i32 s45, s46, 0x2000
	s_add_i32 s44, s46, 0x3000
	s_add_i32 s43, s46, 0x4000
	s_waitcnt lgkmcnt(0)
	v_mfma_f32_16x16x32_bf16 v[192:195], v[96:99], v[74:77], v[88:91]
	ds_read_b128 v[84:87], v129 offset:4096
	s_nop 1
	ds_read_b128 v[88:91], v129 offset:4608
	ds_read_b128 v[92:95], v131 offset:4096
	ds_read_b128 v[96:99], v131 offset:4608
	s_add_i32 s42, s46, 0x5000
	s_waitcnt lgkmcnt(3)
	v_mfma_f32_16x16x32_bf16 v[84:87], v[84:87], v[78:81], 0
	s_add_i32 s41, s46, 0x6000
	s_add_i32 s40, s46, 0x7000
	s_add_u32 s38, s80, s0
	s_waitcnt lgkmcnt(1)
	v_mfma_f32_16x16x32_bf16 v[196:199], v[92:95], v[74:77], v[84:87]
	s_addc_u32 s39, s81, s1
	s_sub_i32 s0, s12, s16
	s_mulk_i32 s0, 0x7c
	v_mfma_f32_16x16x32_bf16 v[84:87], v[88:91], v[78:81], 0
	s_add_i32 s0, s0, 0
	s_add_i32 s0, s0, 0x1e100
	s_waitcnt lgkmcnt(0)
	v_mfma_f32_16x16x32_bf16 v[200:203], v[96:99], v[74:77], v[84:87]
	s_nop 3
	ds_read_b128 v[84:87], v129 offset:8192
	ds_read_b128 v[88:91], v129 offset:8704
	ds_read_b128 v[92:95], v131 offset:8192
	ds_read_b128 v[96:99], v131 offset:8704
	s_waitcnt lgkmcnt(3)
	v_mfma_f32_16x16x32_bf16 v[84:87], v[84:87], v[78:81], 0
	s_waitcnt lgkmcnt(1)
	v_mfma_f32_16x16x32_bf16 v[122:125], v[92:95], v[74:77], v[84:87]
	ds_read_b128 v[92:95], v131 offset:12288
	v_mfma_f32_16x16x32_bf16 v[84:87], v[88:91], v[78:81], 0
	ds_read_b128 v[88:91], v129 offset:12288
	s_waitcnt lgkmcnt(2)
	v_mfma_f32_16x16x32_bf16 v[118:121], v[96:99], v[74:77], v[84:87]
	v_max_i32_e32 v96, 8, v135
	v_add_u32_e32 v137, -8, v96
	ds_read_b128 v[96:99], v131 offset:12800
	s_nop 1
	ds_read_b128 v[82:85], v129 offset:12800
	s_waitcnt lgkmcnt(2)
	v_mfma_f32_16x16x32_bf16 v[86:89], v[88:91], v[78:81], 0
	v_mfma_f32_16x16x32_bf16 v[110:113], v[92:95], v[74:77], v[86:89]
	ds_read_b128 v[90:93], v131 offset:16384
	s_nop 5
	ds_read_b128 v[86:89], v129 offset:16384
	s_waitcnt lgkmcnt(2)
	v_mfma_f32_16x16x32_bf16 v[82:85], v[82:85], v[78:81], 0
	v_mfma_f32_16x16x32_bf16 v[114:117], v[96:99], v[74:77], v[82:85]
	s_nop 6
	ds_read_b128 v[82:85], v129 offset:16896
	ds_read_b128 v[94:97], v131 offset:16896
	ds_read_b128 v[98:101], v129 offset:20480
	ds_read_b128 v[204:207], v129 offset:20992
	s_waitcnt lgkmcnt(4)
	v_mfma_f32_16x16x32_bf16 v[86:89], v[86:89], v[78:81], 0
	s_waitcnt lgkmcnt(3)
	v_mfma_f32_16x16x32_bf16 v[82:85], v[82:85], v[78:81], 0
	v_mfma_f32_16x16x32_bf16 v[102:105], v[90:93], v[74:77], v[86:89]
	s_nop 4
	ds_read_b128 v[86:89], v131 offset:20480
	ds_read_b128 v[90:93], v131 offset:20992
	ds_read_b128 v[208:211], v129 offset:24576
	ds_read_b128 v[212:215], v129 offset:25088
	ds_read_b128 v[216:219], v131 offset:24576
	ds_read_b128 v[220:223], v131 offset:25088
	ds_read_b128 v[224:227], v129 offset:28672
	ds_read_b128 v[228:231], v129 offset:29184
	s_waitcnt lgkmcnt(10)
	v_mfma_f32_16x16x32_bf16 v[106:109], v[94:97], v[74:77], v[82:85]
	ds_read_b128 v[232:235], v131 offset:28672
	ds_read_b128 v[236:239], v131 offset:29184
	v_add_u32_e32 v131, v133, v142
	v_min_u32_e32 v129, 48, v137
	s_waitcnt lgkmcnt(11)
	v_mfma_f32_16x16x32_bf16 v[82:85], v[98:101], v[78:81], 0
	v_cmp_ge_u32_e32 vcc, v131, v129
	v_or_b32_e32 v139, 1, v131
	v_or_b32_e32 v155, 2, v131
	s_waitcnt lgkmcnt(9)
	v_mfma_f32_16x16x32_bf16 v[94:97], v[86:89], v[74:77], v[82:85]
	v_or_b32_e32 v157, 3, v131
	v_mfma_f32_16x16x32_bf16 v[82:85], v[204:207], v[78:81], 0
	s_waitcnt lgkmcnt(8)
	v_mfma_f32_16x16x32_bf16 v[90:93], v[90:93], v[74:77], v[82:85]
	s_waitcnt lgkmcnt(6)
	v_mfma_f32_16x16x32_bf16 v[86:89], v[212:215], v[78:81], 0
	s_nop 3
	v_sub_u32_e32 v82, v131, v135
	v_lshl_add_u32 v133, v82, 2, s0
	ds_read2_b32 v[204:205], v133 offset0:232 offset1:233
	v_add_u32_e32 v135, 16, v129
	v_cmp_lt_u32_e64 s[0:1], v131, v135
	s_and_b64 vcc, vcc, s[0:1]
	v_mfma_f32_16x16x32_bf16 v[82:85], v[208:211], v[78:81], 0
	s_waitcnt lgkmcnt(0)
	v_add_f32_e32 v98, v188, v204
	v_cndmask_b32_e32 v137, v186, v98, vcc
	ds_read2_b32 v[206:207], v133 offset0:234 offset1:235
	ds_read2_b32 v[208:209], v133 offset0:236 offset1:237
	ds_read2_b32 v[210:211], v133 offset0:238 offset1:239
	v_mfma_f32_16x16x32_bf16 v[98:101], v[220:223], v[74:77], v[86:89]
	v_cmp_ge_u32_e64 s[0:1], v139, v129
	v_cmp_lt_u32_e64 s[10:11], v139, v135
	s_and_b64 s[10:11], s[0:1], s[10:11]
	v_mfma_f32_16x16x32_bf16 v[86:89], v[224:227], v[78:81], 0
	v_cmp_ge_u32_e64 s[0:1], v155, v129
	v_cmp_lt_u32_e64 s[12:13], v155, v135
	v_add_f32_e32 v139, v189, v205
	v_mfma_f32_16x16x32_bf16 v[78:81], v[228:231], v[78:81], 0
	s_and_b64 s[12:13], s[0:1], s[12:13]
	v_cmp_ge_u32_e64 s[0:1], v157, v129
	v_cmp_lt_u32_e64 s[14:15], v157, v135
	v_mfma_f32_16x16x32_bf16 v[82:85], v[216:219], v[74:77], v[82:85]
	v_cndmask_b32_e64 v139, v186, v139, s[10:11]
	s_waitcnt lgkmcnt(2)
	v_add_f32_e32 v155, v190, v206
	s_and_b64 s[14:15], s[0:1], s[14:15]
	v_mfma_f32_16x16x32_bf16 v[86:89], v[232:235], v[74:77], v[86:89]
	v_max3_f32 v141, v137, s33, v139
	v_cndmask_b32_e64 v155, v186, v155, s[12:13]
	v_add_u32_e32 v190, 0x434, v133
	v_mfma_f32_16x16x32_bf16 v[74:77], v[236:239], v[74:77], v[78:81]
	s_nop 2
	v_or_b32_e32 v79, 4, v131
	v_add_f32_e32 v78, v191, v207
	v_cmp_ge_u32_e64 s[0:1], v79, v129
	v_cmp_lt_u32_e64 s[16:17], v79, v135
	v_cndmask_b32_e64 v157, v186, v78, s[14:15]
	s_waitcnt lgkmcnt(1)
	v_add_f32_e32 v79, v192, v208
	s_and_b64 s[16:17], s[0:1], s[16:17]
	v_max3_f32 v78, v141, v155, v157
	v_cndmask_b32_e64 v141, v186, v79, s[16:17]
	v_or_b32_e32 v79, 5, v131
	v_cmp_ge_u32_e64 s[0:1], v79, v129
	v_cmp_lt_u32_e64 s[18:19], v79, v135
	v_add_f32_e32 v79, v193, v209
	s_and_b64 s[18:19], s[0:1], s[18:19]
	v_cndmask_b32_e64 v187, v186, v79, s[18:19]
	v_or_b32_e32 v79, 6, v131
	v_cmp_ge_u32_e64 s[0:1], v79, v129
	v_cmp_lt_u32_e64 s[20:21], v79, v135
	s_waitcnt lgkmcnt(0)
	v_add_f32_e32 v79, v194, v210
	s_and_b64 s[20:21], s[0:1], s[20:21]
	v_cndmask_b32_e64 v192, v186, v79, s[20:21]
	v_or_b32_e32 v79, 7, v131
	v_cmp_ge_u32_e64 s[0:1], v79, v129
	v_cmp_lt_u32_e64 s[22:23], v79, v135
	v_add_f32_e32 v79, v195, v211
	s_and_b64 s[22:23], s[0:1], s[22:23]
	v_max3_f32 v78, v78, v141, v187
	v_cndmask_b32_e64 v129, v186, v79, s[22:23]
	v_max3_f32 v131, v78, v192, v129
	v_add_u32_e32 v78, 0x41c, v133
	ds_read2_b32 v[78:79], v78 offset1:1
	v_add_u32_e32 v80, 0x424, v133
	v_add_u32_e32 v135, 0x42c, v133
	ds_read2_b32 v[80:81], v80 offset1:1
	ds_read2_b32 v[188:189], v135 offset1:1
	ds_read2_b32 v[190:191], v190 offset1:1
	s_lshl_b32 s0, s37, 7
	s_waitcnt lgkmcnt(3)
	v_add_f32_e32 v78, v196, v78
	v_cndmask_b32_e32 v135, v186, v78, vcc
	v_add_f32_e32 v78, v197, v79
	v_cndmask_b32_e64 v193, v186, v78, s[10:11]
	s_waitcnt lgkmcnt(2)
	v_add_f32_e32 v79, v198, v80
	v_max3_f32 v78, v131, v135, v193
	v_cndmask_b32_e64 v131, v186, v79, s[12:13]
	v_add_f32_e32 v79, v199, v81
	v_cndmask_b32_e64 v194, v186, v79, s[14:15]
	s_waitcnt lgkmcnt(1)
	v_add_f32_e32 v79, v200, v188
	v_cndmask_b32_e64 v195, v186, v79, s[16:17]
	v_add_f32_e32 v79, v201, v189
	v_cndmask_b32_e64 v196, v186, v79, s[18:19]
	s_waitcnt lgkmcnt(0)
	v_add_f32_e32 v79, v202, v190
	v_max3_f32 v78, v78, v131, v194
	v_cndmask_b32_e64 v197, v186, v79, s[20:21]
	v_add_f32_e32 v79, v203, v191
	v_max3_f32 v78, v78, v195, v196
	v_cndmask_b32_e64 v198, v186, v79, s[22:23]
	v_max3_f32 v199, v78, v197, v198
	v_add_u32_e32 v78, 0x498, v133
	ds_read2_b32 v[78:79], v78 offset1:1
	v_add_u32_e32 v80, 0x4a0, v133
	v_add_u32_e32 v188, 0x4a8, v133
	v_add_u32_e32 v190, 0x4b0, v133
	ds_read2_b32 v[80:81], v80 offset1:1
	ds_read2_b32 v[188:189], v188 offset1:1
	ds_read2_b32 v[190:191], v190 offset1:1
	s_waitcnt lgkmcnt(3)
	v_add_f32_e32 v78, v122, v78
	v_cndmask_b32_e32 v122, v186, v78, vcc
	v_add_f32_e32 v78, v123, v79
	s_waitcnt lgkmcnt(2)
	v_add_f32_e32 v79, v124, v80
	v_cndmask_b32_e64 v124, v186, v79, s[12:13]
	v_add_f32_e32 v79, v125, v81
	v_cndmask_b32_e64 v125, v186, v79, s[14:15]
	s_waitcnt lgkmcnt(1)
	v_add_f32_e32 v79, v118, v188
	v_cndmask_b32_e64 v123, v186, v78, s[10:11]
	v_cndmask_b32_e64 v188, v186, v79, s[16:17]
	v_add_f32_e32 v79, v119, v189
	v_max3_f32 v78, v199, v122, v123
	v_cndmask_b32_e64 v189, v186, v79, s[18:19]
	s_waitcnt lgkmcnt(0)
	v_add_f32_e32 v79, v120, v190
	v_max3_f32 v78, v78, v124, v125
	v_cndmask_b32_e64 v190, v186, v79, s[20:21]
	v_add_f32_e32 v79, v121, v191
	v_max3_f32 v78, v78, v188, v189
	v_cndmask_b32_e64 v191, v186, v79, s[22:23]
	v_max3_f32 v199, v78, v190, v191
	v_add_u32_e32 v78, 0x514, v133
	ds_read2_b32 v[78:79], v78 offset1:1
	v_add_u32_e32 v80, 0x51c, v133
	v_add_u32_e32 v118, 0x524, v133
	v_add_u32_e32 v120, 0x52c, v133
	ds_read2_b32 v[80:81], v80 offset1:1
	ds_read2_b32 v[118:119], v118 offset1:1
	ds_read2_b32 v[120:121], v120 offset1:1
	s_waitcnt lgkmcnt(3)
	v_add_f32_e32 v78, v110, v78
	v_cndmask_b32_e32 v200, v186, v78, vcc
	v_add_f32_e32 v78, v111, v79
	v_cndmask_b32_e64 v201, v186, v78, s[10:11]
	s_waitcnt lgkmcnt(2)
	v_add_f32_e32 v79, v112, v80
	v_max3_f32 v78, v199, v200, v201
	v_cndmask_b32_e64 v199, v186, v79, s[12:13]
	v_add_f32_e32 v79, v113, v81
	v_cndmask_b32_e64 v202, v186, v79, s[14:15]
	s_waitcnt lgkmcnt(1)
	v_add_f32_e32 v79, v114, v118
	v_cndmask_b32_e64 v114, v186, v79, s[16:17]
	v_add_f32_e32 v79, v115, v119
	v_cndmask_b32_e64 v115, v186, v79, s[18:19]
	s_waitcnt lgkmcnt(0)
	v_add_f32_e32 v79, v116, v120
	v_max3_f32 v78, v78, v199, v202
	v_cndmask_b32_e64 v116, v186, v79, s[20:21]
	v_add_f32_e32 v79, v117, v121
	v_max3_f32 v78, v78, v114, v115
	v_cndmask_b32_e64 v117, v186, v79, s[22:23]
	v_max3_f32 v118, v78, v116, v117
	v_add_u32_e32 v78, 0x590, v133
	ds_read2_b32 v[78:79], v78 offset1:1
	v_add_u32_e32 v80, 0x598, v133
	v_add_u32_e32 v110, 0x5a0, v133
	v_add_u32_e32 v112, 0x5a8, v133
	ds_read2_b32 v[80:81], v80 offset1:1
	ds_read2_b32 v[110:111], v110 offset1:1
	ds_read2_b32 v[112:113], v112 offset1:1
	s_waitcnt lgkmcnt(3)
	v_add_f32_e32 v78, v102, v78
	v_cndmask_b32_e32 v119, v186, v78, vcc
	v_add_f32_e32 v78, v103, v79
	v_cndmask_b32_e64 v120, v186, v78, s[10:11]
	s_waitcnt lgkmcnt(2)
	v_add_f32_e32 v79, v104, v80
	v_max3_f32 v78, v118, v119, v120
	v_cndmask_b32_e64 v118, v186, v79, s[12:13]
	v_add_f32_e32 v79, v105, v81
	v_cndmask_b32_e64 v121, v186, v79, s[14:15]
	s_waitcnt lgkmcnt(1)
	v_add_f32_e32 v79, v106, v110
	v_cndmask_b32_e64 v106, v186, v79, s[16:17]
	v_add_f32_e32 v79, v107, v111
	v_cndmask_b32_e64 v107, v186, v79, s[18:19]
	s_waitcnt lgkmcnt(0)
	v_add_f32_e32 v79, v108, v112
	v_max3_f32 v78, v78, v118, v121
	v_cndmask_b32_e64 v108, v186, v79, s[20:21]
	v_add_f32_e32 v79, v109, v113
	v_max3_f32 v78, v78, v106, v107
	v_cndmask_b32_e64 v109, v186, v79, s[22:23]
	v_max3_f32 v110, v78, v108, v109
	v_add_u32_e32 v78, 0x60c, v133
	ds_read2_b32 v[78:79], v78 offset1:1
	v_add_u32_e32 v80, 0x614, v133
	v_add_u32_e32 v102, 0x61c, v133
	v_add_u32_e32 v104, 0x624, v133
	ds_read2_b32 v[80:81], v80 offset1:1
	ds_read2_b32 v[102:103], v102 offset1:1
	ds_read2_b32 v[104:105], v104 offset1:1
	s_waitcnt lgkmcnt(3)
	v_add_f32_e32 v78, v94, v78
	v_cndmask_b32_e32 v94, v186, v78, vcc
	v_add_f32_e32 v78, v95, v79
	s_waitcnt lgkmcnt(2)
	v_add_f32_e32 v79, v96, v80
	v_cndmask_b32_e64 v96, v186, v79, s[12:13]
	v_add_f32_e32 v79, v97, v81
	v_cndmask_b32_e64 v97, v186, v79, s[14:15]
	s_waitcnt lgkmcnt(1)
	v_add_f32_e32 v79, v90, v102
	v_cndmask_b32_e64 v95, v186, v78, s[10:11]
	v_cndmask_b32_e64 v102, v186, v79, s[16:17]
	v_add_f32_e32 v79, v91, v103
	v_max3_f32 v78, v110, v94, v95
	v_cndmask_b32_e64 v103, v186, v79, s[18:19]
	s_waitcnt lgkmcnt(0)
	v_add_f32_e32 v79, v92, v104
	v_max3_f32 v78, v78, v96, v97
	v_cndmask_b32_e64 v104, v186, v79, s[20:21]
	v_add_f32_e32 v79, v93, v105
	v_max3_f32 v78, v78, v102, v103
	v_cndmask_b32_e64 v105, v186, v79, s[22:23]
	v_max3_f32 v110, v78, v104, v105
	v_add_u32_e32 v78, 0x688, v133
	ds_read2_b32 v[78:79], v78 offset1:1
	v_add_u32_e32 v80, 0x690, v133
	v_add_u32_e32 v90, 0x698, v133
	v_add_u32_e32 v92, 0x6a0, v133
	ds_read2_b32 v[80:81], v80 offset1:1
	ds_read2_b32 v[90:91], v90 offset1:1
	ds_read2_b32 v[92:93], v92 offset1:1
	s_waitcnt lgkmcnt(3)
	v_add_f32_e32 v78, v82, v78
	v_cndmask_b32_e32 v111, v186, v78, vcc
	v_add_f32_e32 v78, v83, v79
	v_cndmask_b32_e64 v112, v186, v78, s[10:11]
	s_waitcnt lgkmcnt(2)
	v_add_f32_e32 v79, v84, v80
	v_max3_f32 v78, v110, v111, v112
	v_cndmask_b32_e64 v110, v186, v79, s[12:13]
	v_add_f32_e32 v79, v85, v81
	v_cndmask_b32_e64 v113, v186, v79, s[14:15]
	s_waitcnt lgkmcnt(1)
	v_add_f32_e32 v79, v98, v90
	v_cndmask_b32_e64 v203, v186, v79, s[16:17]
	v_add_f32_e32 v79, v99, v91
	v_cndmask_b32_e64 v204, v186, v79, s[18:19]
	s_waitcnt lgkmcnt(0)
	v_add_f32_e32 v79, v100, v92
	v_max3_f32 v78, v78, v110, v113
	v_cndmask_b32_e64 v205, v186, v79, s[20:21]
	v_add_f32_e32 v79, v101, v93
	v_max3_f32 v78, v78, v203, v204
	v_cndmask_b32_e64 v206, v186, v79, s[22:23]
	v_max3_f32 v90, v78, v205, v206
	v_add_u32_e32 v78, 0x704, v133
	ds_read2_b32 v[78:79], v78 offset1:1
	v_add_u32_e32 v80, 0x70c, v133
	v_add_u32_e32 v82, 0x714, v133
	v_add_u32_e32 v84, 0x71c, v133
	ds_read2_b32 v[80:81], v80 offset1:1
	ds_read2_b32 v[82:83], v82 offset1:1
	ds_read2_b32 v[84:85], v84 offset1:1
	s_waitcnt lgkmcnt(3)
	v_add_f32_e32 v78, v86, v78
	v_cndmask_b32_e32 v133, v186, v78, vcc
	v_add_f32_e32 v78, v87, v79
	s_waitcnt lgkmcnt(2)
	v_add_f32_e32 v79, v88, v80
	v_cndmask_b32_e64 v207, v186, v78, s[10:11]
	v_cndmask_b32_e64 v208, v186, v79, s[12:13]
	v_add_f32_e32 v79, v89, v81
	s_waitcnt lgkmcnt(1)
	v_add_f32_e32 v74, v74, v82
	v_max3_f32 v78, v90, v133, v207
	v_cndmask_b32_e64 v209, v186, v79, s[14:15]
	v_cndmask_b32_e64 v210, v186, v74, s[16:17]
	v_add_f32_e32 v74, v75, v83
	s_waitcnt lgkmcnt(0)
	v_add_f32_e32 v75, v76, v84
	v_max3_f32 v78, v78, v208, v209
	v_cndmask_b32_e64 v211, v186, v74, s[18:19]
	v_cndmask_b32_e64 v212, v186, v75, s[20:21]
	v_add_f32_e32 v75, v77, v85
	v_max3_f32 v74, v78, v210, v211
	v_cndmask_b32_e64 v213, v186, v75, s[22:23]
	v_max3_f32 v74, v74, v212, v213
	ds_bpermute_b32 v75, v179, v74
	v_add_u32_e32 v90, s46, v181
	s_add_u32 s0, s38, s0
	s_addc_u32 s1, s39, 0
	s_mov_b32 s14, s36
	s_waitcnt lgkmcnt(0)
	v_max_f32_e32 v75, v75, v75
	v_max_f32_e32 v74, v74, v75
	ds_bpermute_b32 v75, v180, v74
	s_mov_b32 s15, s35
	s_waitcnt lgkmcnt(0)
	v_max_f32_e32 v75, v75, v75
	v_max_f32_e32 v214, v74, v75
	v_lshlrev_b32_e32 v252, 2, v144
	v_lshl_or_b32 v252, s37, 8, v252
	global_load_dwordx4 v[216:219], v252, s[72:73]
	global_load_dwordx4 v[240:243], v252, s[72:73] offset:64
	global_load_dwordx4 v[244:247], v252, s[72:73] offset:128
	global_load_dwordx4 v[248:251], v252, s[72:73] offset:192
	v_sub_f32_e32 v74, v137, v214
	v_exp_f32_e32 v78, v74
	v_sub_f32_e32 v74, v139, v214
	v_exp_f32_e32 v79, v74
	v_sub_f32_e32 v74, v155, v214
	v_exp_f32_e32 v80, v74
	v_sub_f32_e32 v74, v157, v214
	v_exp_f32_e32 v81, v74
	v_sub_f32_e32 v75, v141, v214
	v_add_f32_e32 v74, 0, v78
	v_exp_f32_e32 v86, v75
	v_sub_f32_e32 v75, v187, v214
	v_add_f32_e32 v74, v79, v74
	v_exp_f32_e32 v87, v75
	v_sub_f32_e32 v75, v192, v214
	v_add_f32_e32 v74, v80, v74
	v_exp_f32_e32 v88, v75
	v_sub_f32_e32 v75, v129, v214
	v_add_f32_e32 v74, v81, v74
	v_exp_f32_e32 v89, v75
	v_sub_f32_e32 v75, v135, v214
	v_add_f32_e32 v74, v86, v74
	v_exp_f32_e32 v98, v75
	v_sub_f32_e32 v75, v193, v214
	v_add_f32_e32 v74, v87, v74
	v_exp_f32_e32 v99, v75
	v_sub_f32_e32 v75, v131, v214
	v_add_f32_e32 v74, v88, v74
	v_exp_f32_e32 v129, v75
	v_sub_f32_e32 v75, v194, v214
	v_add_f32_e32 v74, v89, v74
	v_exp_f32_e32 v131, v75
	v_sub_f32_e32 v75, v195, v214
	v_add_f32_e32 v74, v98, v74
	v_exp_f32_e32 v135, v75
	v_sub_f32_e32 v75, v196, v214
	v_add_f32_e32 v74, v99, v74
	v_exp_f32_e32 v137, v75
	v_sub_f32_e32 v75, v197, v214
	v_add_f32_e32 v74, v129, v74
	v_exp_f32_e32 v139, v75
	v_sub_f32_e32 v75, v198, v214
	v_add_f32_e32 v74, v131, v74
	v_exp_f32_e32 v141, v75
	v_sub_f32_e32 v75, v122, v214
	v_add_f32_e32 v74, v135, v74
	v_exp_f32_e32 v122, v75
	v_sub_f32_e32 v75, v123, v214
	v_add_f32_e32 v74, v137, v74
	v_exp_f32_e32 v123, v75
	v_sub_f32_e32 v75, v124, v214
	v_add_f32_e32 v74, v139, v74
	v_exp_f32_e32 v124, v75
	v_sub_f32_e32 v75, v125, v214
	v_add_f32_e32 v74, v141, v74
	v_exp_f32_e32 v125, v75
	v_sub_f32_e32 v75, v188, v214
	v_add_f32_e32 v74, v122, v74
	v_exp_f32_e32 v155, v75
	v_sub_f32_e32 v75, v189, v214
	v_add_f32_e32 v74, v123, v74
	v_exp_f32_e32 v157, v75
	v_sub_f32_e32 v75, v190, v214
	v_add_f32_e32 v74, v124, v74
	v_exp_f32_e32 v187, v75
	v_sub_f32_e32 v75, v191, v214
	v_add_f32_e32 v74, v125, v74
	v_exp_f32_e32 v188, v75
	v_sub_f32_e32 v75, v200, v214
	v_add_f32_e32 v74, v155, v74
	v_exp_f32_e32 v189, v75
	v_sub_f32_e32 v75, v201, v214
	v_add_f32_e32 v74, v157, v74
	v_exp_f32_e32 v190, v75
	v_sub_f32_e32 v75, v199, v214
	v_add_f32_e32 v74, v187, v74
	v_exp_f32_e32 v191, v75
	v_sub_f32_e32 v75, v202, v214
	v_add_f32_e32 v74, v188, v74
	v_exp_f32_e32 v192, v75
	v_sub_f32_e32 v75, v114, v214
	v_add_f32_e32 v74, v189, v74
	v_exp_f32_e32 v114, v75
	v_sub_f32_e32 v75, v115, v214
	v_add_f32_e32 v74, v190, v74
	v_exp_f32_e32 v115, v75
	v_sub_f32_e32 v75, v116, v214
	v_add_f32_e32 v74, v191, v74
	v_exp_f32_e32 v116, v75
	v_sub_f32_e32 v75, v117, v214
	v_add_f32_e32 v74, v192, v74
	v_exp_f32_e32 v117, v75
	v_sub_f32_e32 v75, v119, v214
	v_add_f32_e32 v74, v114, v74
	v_exp_f32_e32 v119, v75
	v_sub_f32_e32 v75, v120, v214
	v_add_f32_e32 v74, v115, v74
	v_exp_f32_e32 v120, v75
	v_sub_f32_e32 v75, v118, v214
	v_add_f32_e32 v74, v116, v74
	v_exp_f32_e32 v118, v75
	v_sub_f32_e32 v75, v121, v214
	v_add_f32_e32 v74, v117, v74
	v_exp_f32_e32 v121, v75
	v_sub_f32_e32 v75, v106, v214
	v_add_f32_e32 v74, v119, v74
	v_exp_f32_e32 v106, v75
	v_sub_f32_e32 v75, v107, v214
	v_add_f32_e32 v74, v120, v74
	v_exp_f32_e32 v107, v75
	v_sub_f32_e32 v75, v108, v214
	v_add_f32_e32 v74, v118, v74
	v_exp_f32_e32 v108, v75
	v_sub_f32_e32 v75, v109, v214
	v_add_f32_e32 v74, v121, v74
	v_exp_f32_e32 v109, v75
	v_sub_f32_e32 v75, v94, v214
	v_add_f32_e32 v74, v106, v74
	v_exp_f32_e32 v193, v75
	v_sub_f32_e32 v75, v95, v214
	v_add_f32_e32 v74, v107, v74
	v_exp_f32_e32 v194, v75
	v_sub_f32_e32 v75, v96, v214
	v_add_f32_e32 v74, v108, v74
	v_exp_f32_e32 v195, v75
	v_sub_f32_e32 v75, v97, v214
	v_add_f32_e32 v74, v109, v74
	v_exp_f32_e32 v196, v75
	v_add_f32_e32 v74, v193, v74
	v_add_f32_e32 v74, v194, v74
	v_add_f32_e32 v74, v195, v74
	v_add_f32_e32 v82, v196, v74
	v_sub_f32_e32 v74, v102, v214
	v_exp_f32_e32 v102, v74
	v_sub_f32_e32 v74, v103, v214
	v_exp_f32_e32 v103, v74
	v_sub_f32_e32 v91, v104, v214
	v_exp_f32_e32 v104, v91
	v_sub_f32_e32 v91, v105, v214
	v_exp_f32_e32 v105, v91
	v_add_f32_e32 v82, v102, v82
	v_add_f32_e32 v94, v103, v82
	v_add_f32_e32 v94, v104, v94
	v_sub_f32_e32 v100, v111, v214
	v_add_u32_e32 v111, s47, v181
	ds_read_b128 v[74:77], v90 offset:61440
	ds_read_b128 v[82:85], v90 offset:62464
	v_cvt_pk_bf16_f32 v78, v78, v79
	v_cvt_pk_bf16_f32 v79, v80, v81
	v_cvt_pk_bf16_f32 v80, v86, v87
	v_cvt_pk_bf16_f32 v81, v88, v89
	ds_read_b128 v[86:89], v90 offset:63488
	v_add_f32_e32 v197, v105, v94
	ds_read_b128 v[94:97], v111 offset:61440
	ds_read_b128 v[90:93], v90 offset:64512
	s_waitcnt lgkmcnt(4)
	v_mfma_f32_16x16x32_bf16 v[74:77], v[74:77], v[78:81], 0
	v_exp_f32_e32 v198, v100
	v_sub_f32_e32 v112, v112, v214
	v_exp_f32_e32 v112, v112
	s_waitcnt lgkmcnt(3)
	v_mfma_f32_16x16x32_bf16 v[82:85], v[82:85], v[78:81], 0
	v_sub_f32_e32 v110, v110, v214
	v_exp_f32_e32 v110, v110
	v_sub_f32_e32 v113, v113, v214
	s_waitcnt lgkmcnt(2)
	v_mfma_f32_16x16x32_bf16 v[86:89], v[86:89], v[78:81], 0
	v_exp_f32_e32 v113, v113
	s_waitcnt lgkmcnt(0)
	v_mfma_f32_16x16x32_bf16 v[78:81], v[90:93], v[78:81], 0
	v_cvt_pk_bf16_f32 v90, v98, v99
	ds_read_b128 v[98:101], v111 offset:62464
	v_cvt_pk_bf16_f32 v91, v129, v131
	v_cvt_pk_bf16_f32 v92, v135, v137
	v_cvt_pk_bf16_f32 v93, v139, v141
	v_add_u32_e32 v129, s45, v181
	s_nop 0
	v_mfma_f32_16x16x32_bf16 v[74:77], v[94:97], v[90:93], v[74:77]
	ds_read_b128 v[94:97], v111 offset:63488
	s_waitcnt lgkmcnt(1)
	v_mfma_f32_16x16x32_bf16 v[82:85], v[98:101], v[90:93], v[82:85]
	ds_read_b128 v[98:101], v111 offset:64512
	s_waitcnt lgkmcnt(1)
	v_mfma_f32_16x16x32_bf16 v[86:89], v[94:97], v[90:93], v[86:89]
	ds_read_b128 v[94:97], v129 offset:61440
	v_add_f32_e32 v111, v198, v197
	v_add_f32_e32 v111, v112, v111
	s_waitcnt lgkmcnt(1)
	v_mfma_f32_16x16x32_bf16 v[78:81], v[98:101], v[90:93], v[78:81]
	ds_read_b128 v[98:101], v129 offset:62464
	v_cvt_pk_bf16_f32 v90, v122, v123
	v_cvt_pk_bf16_f32 v91, v124, v125
	v_cvt_pk_bf16_f32 v92, v155, v157
	v_cvt_pk_bf16_f32 v93, v187, v188
	v_add_u32_e32 v124, s44, v181
	v_sub_f32_e32 v122, v203, v214
	s_waitcnt lgkmcnt(1)
	v_mfma_f32_16x16x32_bf16 v[74:77], v[94:97], v[90:93], v[74:77]
	ds_read_b128 v[94:97], v129 offset:63488
	v_exp_f32_e32 v122, v122
	v_sub_f32_e32 v123, v204, v214
	s_waitcnt lgkmcnt(1)
	v_mfma_f32_16x16x32_bf16 v[82:85], v[98:101], v[90:93], v[82:85]
	ds_read_b128 v[98:101], v129 offset:64512
	v_exp_f32_e32 v123, v123
	v_sub_f32_e32 v125, v205, v214
	s_waitcnt lgkmcnt(1)
	v_mfma_f32_16x16x32_bf16 v[86:89], v[94:97], v[90:93], v[86:89]
	ds_read_b128 v[94:97], v124 offset:61440
	v_add_f32_e32 v111, v110, v111
	v_add_f32_e32 v111, v113, v111
	s_waitcnt lgkmcnt(1)
	v_mfma_f32_16x16x32_bf16 v[78:81], v[98:101], v[90:93], v[78:81]
	ds_read_b128 v[98:101], v124 offset:62464
	v_cvt_pk_bf16_f32 v90, v189, v190
	v_cvt_pk_bf16_f32 v91, v191, v192
	v_cvt_pk_bf16_f32 v92, v114, v115
	v_cvt_pk_bf16_f32 v93, v116, v117
	v_add_u32_e32 v117, s43, v181
	v_exp_f32_e32 v114, v125
	s_waitcnt lgkmcnt(1)
	v_mfma_f32_16x16x32_bf16 v[74:77], v[94:97], v[90:93], v[74:77]
	ds_read_b128 v[94:97], v124 offset:63488
	v_sub_f32_e32 v115, v206, v214
	v_exp_f32_e32 v115, v115
	s_waitcnt lgkmcnt(1)
	v_mfma_f32_16x16x32_bf16 v[82:85], v[98:101], v[90:93], v[82:85]
	ds_read_b128 v[98:101], v124 offset:64512
	v_sub_f32_e32 v116, v133, v214
	v_add_f32_e32 v111, v122, v111
	s_waitcnt lgkmcnt(1)
	v_mfma_f32_16x16x32_bf16 v[86:89], v[94:97], v[90:93], v[86:89]
	ds_read_b128 v[94:97], v117 offset:61440
	v_exp_f32_e32 v116, v116
	v_add_f32_e32 v111, v123, v111
	s_waitcnt lgkmcnt(1)
	v_mfma_f32_16x16x32_bf16 v[78:81], v[98:101], v[90:93], v[78:81]
	ds_read_b128 v[98:101], v117 offset:62464
	v_cvt_pk_bf16_f32 v90, v119, v120
	v_cvt_pk_bf16_f32 v91, v118, v121
	v_cvt_pk_bf16_f32 v92, v106, v107
	v_cvt_pk_bf16_f32 v93, v108, v109
	v_add_u32_e32 v109, s42, v181
	v_add_f32_e32 v111, v114, v111
	s_waitcnt lgkmcnt(1)
	v_mfma_f32_16x16x32_bf16 v[74:77], v[94:97], v[90:93], v[74:77]
	ds_read_b128 v[94:97], v117 offset:63488
	v_sub_f32_e32 v124, v207, v214
	v_add_f32_e32 v111, v115, v111
	s_waitcnt lgkmcnt(1)
	v_mfma_f32_16x16x32_bf16 v[82:85], v[98:101], v[90:93], v[82:85]
	ds_read_b128 v[98:101], v117 offset:64512
	v_exp_f32_e32 v106, v124
	v_sub_f32_e32 v107, v208, v214
	s_waitcnt lgkmcnt(1)
	v_mfma_f32_16x16x32_bf16 v[86:89], v[94:97], v[90:93], v[86:89]
	ds_read_b128 v[94:97], v109 offset:61440
	v_exp_f32_e32 v107, v107
	v_add_f32_e32 v108, v116, v111
	s_waitcnt lgkmcnt(1)
	v_mfma_f32_16x16x32_bf16 v[78:81], v[98:101], v[90:93], v[78:81]
	ds_read_b128 v[98:101], v109 offset:62464
	v_cvt_pk_bf16_f32 v90, v193, v194
	v_cvt_pk_bf16_f32 v91, v195, v196
	v_cvt_pk_bf16_f32 v92, v102, v103
	v_cvt_pk_bf16_f32 v93, v104, v105
	v_add_u32_e32 v105, s41, v181
	v_sub_f32_e32 v111, v209, v214
	s_waitcnt lgkmcnt(1)
	v_mfma_f32_16x16x32_bf16 v[74:77], v[94:97], v[90:93], v[74:77]
	ds_read_b128 v[94:97], v109 offset:63488
	v_exp_f32_e32 v111, v111
	v_add_f32_e32 v108, v106, v108
	s_waitcnt lgkmcnt(1)
	v_mfma_f32_16x16x32_bf16 v[82:85], v[98:101], v[90:93], v[82:85]
	ds_read_b128 v[98:101], v109 offset:64512
	v_sub_f32_e32 v102, v210, v214
	v_add_f32_e32 v108, v107, v108
	s_waitcnt lgkmcnt(1)
	v_mfma_f32_16x16x32_bf16 v[86:89], v[94:97], v[90:93], v[86:89]
	ds_read_b128 v[94:97], v105 offset:61440
	v_exp_f32_e32 v102, v102
	v_sub_f32_e32 v104, v211, v214
	s_waitcnt lgkmcnt(1)
	v_mfma_f32_16x16x32_bf16 v[78:81], v[98:101], v[90:93], v[78:81]
	ds_read_b128 v[98:101], v105 offset:62464
	v_add_f32_e32 v103, v111, v108
	v_exp_f32_e32 v104, v104
	v_sub_f32_e32 v108, v212, v214
	v_cvt_pk_bf16_f32 v90, v198, v112
	v_cvt_pk_bf16_f32 v91, v110, v113
	v_cvt_pk_bf16_f32 v92, v122, v123
	v_cvt_pk_bf16_f32 v93, v114, v115
	v_exp_f32_e32 v108, v108
	v_sub_f32_e32 v109, v213, v214
	s_waitcnt lgkmcnt(1)
	v_mfma_f32_16x16x32_bf16 v[74:77], v[94:97], v[90:93], v[74:77]
	ds_read_b128 v[94:97], v105 offset:63488
	v_exp_f32_e32 v109, v109
	v_add_f32_e32 v103, v102, v103
	s_waitcnt lgkmcnt(1)
	v_mfma_f32_16x16x32_bf16 v[82:85], v[98:101], v[90:93], v[82:85]
	ds_read_b128 v[98:101], v105 offset:64512
	v_add_f32_e32 v103, v104, v103
	v_add_f32_e32 v103, v108, v103
	v_add_f32_e32 v103, v109, v103
	ds_bpermute_b32 v105, v179, v103
	s_waitcnt lgkmcnt(1)
	v_mfma_f32_16x16x32_bf16 v[78:81], v[98:101], v[90:93], v[78:81]
	v_cvt_pk_bf16_f32 v100, v102, v104
	v_lshlrev_b32_e32 v102, 2, v144
	v_lshl_or_b32 v120, s37, 8, v102
	s_waitcnt lgkmcnt(0)
	v_add_f32_e32 v112, v103, v105
	v_add_u32_e32 v110, s40, v181
	v_mfma_f32_16x16x32_bf16 v[86:89], v[94:97], v[90:93], v[86:89]
	ds_read_b128 v[94:97], v110 offset:61440
	ds_read_b128 v[90:93], v110 offset:62464
	v_cvt_pk_bf16_f32 v98, v116, v106
	v_cvt_pk_bf16_f32 v99, v107, v111
	v_cvt_pk_bf16_f32 v101, v108, v109
	ds_bpermute_b32 v106, v180, v112
	v_and_b32_e32 v113, 0xffff0000, v163
	s_waitcnt lgkmcnt(2)
	v_mfma_f32_16x16x32_bf16 v[94:97], v[94:97], v[98:101], v[74:77]
	v_mov_b32_e32 v157, v127
	s_nop 1
	ds_read_b128 v[74:77], v110 offset:63488
	s_waitcnt lgkmcnt(2)
	v_mfma_f32_16x16x32_bf16 v[82:85], v[90:93], v[98:101], v[82:85]
	ds_read_b128 v[90:93], v110 offset:64512
	s_waitcnt lgkmcnt(1)
	v_mfma_f32_16x16x32_bf16 v[86:89], v[74:77], v[98:101], v[86:89]
	v_add_f32_e32 v74, v112, v106
	v_rcp_f32_e32 v106, v74
	v_lshlrev_b32_e32 v112, 16, v163
	s_waitcnt lgkmcnt(0)
	v_mfma_f32_16x16x32_bf16 v[76:79], v[90:93], v[98:101], v[78:81]
	v_lshlrev_b32_e32 v100, 16, v162
	v_pk_mul_f32 v[96:97], v[96:97], v[106:107] op_sel_hi:[1,0]
	v_pk_mul_f32 v[94:95], v[94:95], v[106:107] op_sel_hi:[1,0]
	v_and_b32_e32 v101, 0xffff0000, v162
	v_mul_f32_e32 v108, 0xbfb8aa3b, v101
	s_nop 2
	v_pk_mul_f32 v[76:77], v[76:77], v[106:107] op_sel_hi:[1,0]
	v_pk_mul_f32 v[74:75], v[78:79], v[106:107] op_sel_hi:[1,0]
	v_mul_f32_e32 v107, 0xbfb8aa3b, v100
	v_exp_f32_e32 v107, v107
	v_exp_f32_e32 v111, v108
	v_pk_mul_f32 v[108:109], v[94:95], v[94:95]
	v_pk_mul_f32 v[98:99], v[96:97], v[96:97]
	v_add_f32_e32 v107, 1.0, v107
	v_rcp_f32_e32 v110, v107
	v_add_f32_e32 v107, 1.0, v111
	v_add_f32_e32 v108, v108, v109
	v_pk_mul_f32 v[82:83], v[82:83], v[106:107] op_sel_hi:[1,0]
	v_add_f32_e32 v98, v98, v108
	v_pk_mul_f32 v[116:117], v[82:83], v[82:83]
	v_add_f32_e32 v98, v99, v98
	v_pk_mul_f32 v[84:85], v[84:85], v[106:107] op_sel_hi:[1,0]
	v_add_f32_e32 v98, v116, v98
	v_pk_mul_f32 v[114:115], v[84:85], v[84:85]
	v_add_f32_e32 v98, v117, v98
	v_pk_mul_f32 v[86:87], v[86:87], v[106:107] op_sel_hi:[1,0]
	v_add_f32_e32 v98, v114, v98
	v_rcp_f32_e32 v111, v107
	v_pk_mul_f32 v[88:89], v[88:89], v[106:107] op_sel_hi:[1,0]
	v_pk_mul_f32 v[106:107], v[86:87], v[86:87]
	v_add_f32_e32 v98, v115, v98
	v_add_f32_e32 v98, v106, v98
	v_pk_mul_f32 v[118:119], v[88:89], v[88:89]
	v_add_f32_e32 v98, v107, v98
	v_add_f32_e32 v98, v118, v98
	v_pk_mul_f32 v[80:81], v[76:77], v[76:77]
	v_add_f32_e32 v98, v119, v98
	v_add_f32_e32 v80, v80, v98
	v_pk_mul_f32 v[78:79], v[74:75], v[74:75]
	v_add_f32_e32 v80, v81, v80
	v_add_f32_e32 v78, v78, v80
	v_add_f32_e32 v78, v79, v78
	ds_bpermute_b32 v79, v179, v78
	v_mul_f32_e32 v80, 0xbfb8aa3b, v112
	v_exp_f32_e32 v80, v80
	v_mul_f32_e32 v81, 0xbfb8aa3b, v113
	v_exp_f32_e32 v81, v81
	s_waitcnt lgkmcnt(0)
	v_add_f32_e32 v98, v78, v79
	ds_bpermute_b32 v99, v180, v98
	v_add_f32_e32 v78, 1.0, v80
	v_add_f32_e32 v79, 1.0, v81
	v_lshl_add_u64 v[90:91], s[0:1], 0, v[156:157]
	v_lshlrev_b32_e32 v92, 1, v144
	s_waitcnt lgkmcnt(0)
	v_add_f32_e32 v80, v98, v99
	v_fmamk_f32 v80, v80, 0x3c800000, v185
	v_mul_f32_e32 v81, 0x4b800000, v80
	v_cmp_gt_f32_e32 vcc, s34, v80
	v_mov_b32_e32 v93, v127
	v_lshl_add_u64 v[90:91], v[90:91], 0, v[92:93]
	v_cndmask_b32_e32 v80, v80, v81, vcc
	v_rsq_f32_e32 v98, v80
	v_rcp_f32_e32 v78, v78
	v_rcp_f32_e32 v79, v79
	v_pk_mul_f32 v[80:81], v[110:111], v[100:101]
	v_mul_f32_e32 v92, 0x45800000, v98
	v_cndmask_b32_e32 v92, v98, v92, vcc
	v_pk_mul_f32 v[94:95], v[94:95], v[92:93] op_sel_hi:[1,0]
	v_pk_mul_f32 v[78:79], v[78:79], v[112:113]
	s_waitcnt vmcnt(0)
	v_pk_mul_f32 v[94:95], v[216:217], v[94:95]
	v_lshlrev_b32_e32 v98, 16, v161
	v_pk_mul_f32 v[80:81], v[80:81], v[94:95]
	v_pk_mul_f32 v[94:95], v[96:97], v[92:93] op_sel_hi:[1,0]
	v_cvt_pk_bf16_f32 v80, v80, v81
	v_pk_mul_f32 v[94:95], v[218:219], v[94:95]
	v_and_b32_e32 v99, 0xffff0000, v161
	v_pk_mul_f32 v[78:79], v[78:79], v[94:95]
	v_lshlrev_b32_e32 v94, 16, v160
	v_cvt_pk_bf16_f32 v81, v78, v79
	global_store_dwordx2 v[90:91], v[80:81], off
	v_and_b32_e32 v95, 0xffff0000, v160
	v_mul_f32_e32 v93, 0xbfb8aa3b, v94
	v_exp_f32_e32 v93, v93
	v_mul_f32_e32 v96, 0xbfb8aa3b, v95
	v_exp_f32_e32 v97, v96
	s_and_b64 vcc, exec, s[28:29]
	v_add_f32_e32 v93, 1.0, v93
	v_rcp_f32_e32 v96, v93
	v_add_f32_e32 v93, 1.0, v97
	v_mul_f32_e32 v97, 0xbfb8aa3b, v98
	v_exp_f32_e32 v100, v97
	v_mul_f32_e32 v97, 0xbfb8aa3b, v99
	v_exp_f32_e32 v101, v97
	v_rcp_f32_e32 v97, v93
	v_add_f32_e32 v93, 1.0, v100
	v_rcp_f32_e32 v100, v93
	v_add_f32_e32 v93, 1.0, v101
	v_rcp_f32_e32 v101, v93
	v_pk_mul_f32 v[82:83], v[82:83], v[92:93] op_sel_hi:[1,0]
	v_pk_mul_f32 v[94:95], v[96:97], v[94:95]
	v_pk_mul_f32 v[76:77], v[76:77], v[92:93] op_sel_hi:[1,0]
	v_pk_mul_f32 v[96:97], v[100:101], v[98:99]
	v_pk_mul_f32 v[74:75], v[74:75], v[92:93] op_sel_hi:[1,0]
	v_mov_b64_e32 v[160:161], v[166:167]
	v_mov_b64_e32 v[162:163], v[164:165]
	v_pk_mul_f32 v[78:79], v[240:241], v[82:83]
	v_pk_mul_f32 v[82:83], v[84:85], v[92:93] op_sel_hi:[1,0]
	v_pk_mul_f32 v[78:79], v[94:95], v[78:79]
	v_pk_mul_f32 v[80:81], v[242:243], v[82:83]
	v_cvt_pk_bf16_f32 v78, v78, v79
	v_pk_mul_f32 v[80:81], v[96:97], v[80:81]
	v_lshlrev_b32_e32 v82, 16, v158
	v_cvt_pk_bf16_f32 v79, v80, v81
	global_store_dwordx2 v[90:91], v[78:79], off offset:32
	v_and_b32_e32 v83, 0xffff0000, v158
	v_mul_f32_e32 v84, 0xbfb8aa3b, v82
	v_mul_f32_e32 v85, 0xbfb8aa3b, v83
	v_exp_f32_e32 v84, v84
	v_exp_f32_e32 v85, v85
	v_add_f32_e32 v84, 1.0, v84
	v_add_f32_e32 v85, 1.0, v85
	v_rcp_f32_e32 v84, v84
	v_rcp_f32_e32 v85, v85
	s_nop 0
	v_pk_mul_f32 v[82:83], v[84:85], v[82:83]
	v_pk_mul_f32 v[84:85], v[86:87], v[92:93] op_sel_hi:[1,0]
	v_pk_mul_f32 v[78:79], v[244:245], v[84:85]
	v_lshlrev_b32_e32 v84, 16, v159
	v_and_b32_e32 v85, 0xffff0000, v159
	v_mul_f32_e32 v86, 0xbfb8aa3b, v84
	v_mul_f32_e32 v87, 0xbfb8aa3b, v85
	v_exp_f32_e32 v86, v86
	v_exp_f32_e32 v87, v87
	v_pk_mul_f32 v[78:79], v[82:83], v[78:79]
	v_mov_b64_e32 v[158:159], v[168:169]
	v_add_f32_e32 v82, 1.0, v86
	v_add_f32_e32 v83, 1.0, v87
	v_rcp_f32_e32 v82, v82
	v_rcp_f32_e32 v83, v83
	v_pk_mul_f32 v[86:87], v[88:89], v[92:93] op_sel_hi:[1,0]
	v_cvt_pk_bf16_f32 v78, v78, v79
	v_pk_mul_f32 v[80:81], v[246:247], v[86:87]
	v_pk_mul_f32 v[82:83], v[82:83], v[84:85]
	s_nop 0
	v_pk_mul_f32 v[80:81], v[82:83], v[80:81]
	v_lshlrev_b32_e32 v82, 16, v146
	v_cvt_pk_bf16_f32 v79, v80, v81
	global_store_dwordx2 v[90:91], v[78:79], off offset:64
	v_and_b32_e32 v83, 0xffff0000, v146
	v_mul_f32_e32 v84, 0xbfb8aa3b, v82
	v_mul_f32_e32 v85, 0xbfb8aa3b, v83
	v_exp_f32_e32 v84, v84
	v_exp_f32_e32 v85, v85
	v_add_f32_e32 v84, 1.0, v84
	v_add_f32_e32 v85, 1.0, v85
	v_rcp_f32_e32 v84, v84
	v_rcp_f32_e32 v85, v85
	v_pk_mul_f32 v[76:77], v[248:249], v[76:77]
	v_pk_mul_f32 v[78:79], v[84:85], v[82:83]
	v_lshlrev_b32_e32 v82, 16, v147
	v_and_b32_e32 v83, 0xffff0000, v147
	v_mul_f32_e32 v84, 0xbfb8aa3b, v82
	v_mul_f32_e32 v85, 0xbfb8aa3b, v83
	v_exp_f32_e32 v84, v84
	v_exp_f32_e32 v85, v85
	v_pk_mul_f32 v[76:77], v[78:79], v[76:77]
	v_pk_mul_f32 v[74:75], v[250:251], v[74:75]
	v_add_f32_e32 v78, 1.0, v84
	v_add_f32_e32 v79, 1.0, v85
	v_rcp_f32_e32 v78, v78
	v_rcp_f32_e32 v79, v79
	v_cvt_pk_bf16_f32 v76, v76, v77
	v_mov_b64_e32 v[146:147], v[170:171]
	v_pk_mul_f32 v[78:79], v[78:79], v[82:83]
	s_nop 0
	v_pk_mul_f32 v[74:75], v[78:79], v[74:75]
	v_mov_b64_e32 v[80:81], v[68:69]
	v_cvt_pk_bf16_f32 v77, v74, v75
	global_store_dwordx2 v[90:91], v[76:77], off offset:96
	v_mov_b64_e32 v[76:77], v[72:73]
	v_mov_b64_e32 v[74:75], v[70:71]
	v_mov_b64_e32 v[78:79], v[66:67]
	s_cbranch_vccnz .LBB0_461
